# hgrn_a loop: thread-0 ticket wait no longer drains the unit's last two stores (vmcnt(2))
# baseline (speedup 1.0000x reference)
; #define LAS __attribute__((address_space(3)))
; __device__ __forceinline__ u32x4 pack8(const float* o) { u32x4 v; v.x = cvt_pk_bf16(o[0], o[1]); v.y = cvt_pk_bf16(o[2], o[3]); v.z = cvt_pk_bf16(o[4], o[5]); v.w = cvt_pk_bf16(o[6], o[7]); return v; }
; __device__ __forceinline__ u32x2 pack4(const f32x4 a) { u32x2 v; v.x = cvt_pk_bf16(a[0], a[1]); v.y = cvt_pk_bf16(a[2], a[3]); return v; }
; #define LBAR() do { asm volatile("s_waitcnt lgkmcnt(0)" ::: "memory"); __builtin_amdgcn_s_barrier(); asm volatile("" ::: "memory"); } while (0)
; #define MFMA16(a, b, c) __builtin_amdgcn_mfma_f32_16x16x32_bf16((a), (b), (c), 0, 0, 0)
; __device__ __forceinline__ void hgrn_a_unit(LAS unsigned char* lds, KP& P_, int l, int bc, int h, const HgRaw& in) {
;     ...
;     { float kd[8];
; #pragma unroll
;       for (int j = 0; j < 8; ++j) { const float G = Gf[t * 65 + k0 + j], Gl = Gf[63 * 65 + k0 + j]; kd[j] = kk[j] * __builtin_amdgcn_exp2f(Gl - G); }
;       if (t == 63) { f32x4 d0, d1;
; #pragma unroll
;           for (int j = 0; j < 4; ++j) { d0[j] = __builtin_amdgcn_exp2f(Gf[63 * 65 + k0 + j]); d1[j] = __builtin_amdgcn_exp2f(Gf[63 * 65 + k0 + 4 + j]); }
;           float* dp = (float*)(p.ws + WS_DECH) + ((size_t)bc * 6 + h) * 64 + k0; *(f32x4*)dp = d0; *(f32x4*)(dp + 4) = d1; }
;       *(LAS u32x4*)(KT + t * 72 + k0) = pack8(kd); }
;     LBAR();
;     { const int wid = tid >> 6, lane = tid & 63, fr = lane & 15, fq = lane >> 4, kt = wid >> 1;
;       bf16_t* sth = (bf16_t*)(p.ws + WS_STH) + ((size_t)bc * 6 + h) * 4096;
; #pragma unroll
;       for (int q = 0; q < 2; ++q) { const int vt = (wid & 1) * 2 + q; f32x4 acc = (f32x4){0.f, 0.f, 0.f, 0.f};
; #pragma unroll
;           for (int ks = 0; ks < 2; ++ks) { const unsigned ro = (unsigned)((32 * ks + 8 * fq + (fr >> 2)) * 144 + 8 * (fr & 3));
;               const unsigned ka = (unsigned)(size_t)KT + ro + 32u * kt, va = (unsigned)(size_t)VT + ro + 32u * vt;
;               const bf16x8 a = tr_frag(ka, ka + 576u), b = tr_frag(va, va + 576u); acc = MFMA16(a, b, acc); }
;           *(u32x2*)(sth + (size_t)(vt * 16 + fr) * 64 + kt * 16 + fq * 4) = pack4(acc); } }
;     LBAR();
; template <int WHICH>
; __device__ void phase_mix_dyn(LAS unsigned char* lds, KP& P0, int l0) {
;     ...
;         if (un >= NMIXU) break;
;         if (tid0 == 0) { tick[0] = n1; tick[1] = n2; }
;         LBAR();
;         u = tick[0]; un = tick[1];
.LBB0_705:
	s_or_b64 exec, exec, s[42:43]
	s_waitcnt lgkmcnt(0)
	v_sub_f32_e32 v0, v57, v55
	v_exp_f32_e32 v55, v0
	v_sub_f32_e32 v0, v56, v54
	v_pk_add_f32 v[46:47], v[46:47], 1.0 op_sel_hi:[1,0] neg_lo:[1,0] neg_hi:[1,0]
	v_exp_f32_e32 v54, v0
	v_sub_f32_e32 v0, v53, v51
	v_pk_mul_f32 v[28:29], v[28:29], v[46:47]
	v_exp_f32_e32 v47, v0
	v_sub_f32_e32 v0, v52, v50
	v_exp_f32_e32 v46, v0
	v_sub_f32_e32 v0, v49, v31
	v_exp_f32_e32 v31, v0
	v_sub_f32_e32 v0, v48, v30
	v_exp_f32_e32 v30, v0
	v_sub_f32_e32 v0, v27, v25
	v_exp_f32_e32 v25, v0
	v_sub_f32_e32 v0, v26, v24
	v_pk_add_f32 v[42:43], v[42:43], 1.0 op_sel_hi:[1,0] neg_lo:[1,0] neg_hi:[1,0]
	v_exp_f32_e32 v24, v0
	v_pk_mul_f32 v[32:33], v[32:33], v[42:43]
	v_pk_add_f32 v[34:35], v[34:35], 1.0 op_sel_hi:[1,0] neg_lo:[1,0] neg_hi:[1,0]
	v_pk_mul_f32 v[26:27], v[32:33], v[30:31]
	v_pk_add_f32 v[30:31], v[36:37], 1.0 op_sel_hi:[1,0] neg_lo:[1,0] neg_hi:[1,0]
	v_pk_mul_f32 v[34:35], v[44:45], v[34:35]
	v_pk_mul_f32 v[30:31], v[38:39], v[30:31]
	v_pk_mul_f32 v[28:29], v[28:29], v[54:55]
	v_pk_mul_f32 v[34:35], v[34:35], v[46:47]
	v_pk_mul_f32 v[24:25], v[30:31], v[24:25]
	v_lshrrev_b32_e32 v0, 5, v60
	v_cvt_pk_bf16_f32 v24, v24, v25
	v_cvt_pk_bf16_f32 v25, v26, v27
	v_cvt_pk_bf16_f32 v26, v34, v35
	v_cvt_pk_bf16_f32 v27, v28, v29
	ds_write_b128 v61, v[24:27] offset:18688
	s_waitcnt lgkmcnt(0)
	s_barrier
	s_mov_b64 s[14:15], s[72:73]
	v_ashrrev_i32_e32 v26, 7, v60
	v_and_b32_e32 v39, 2, v0
	v_lshrrev_b32_e32 v0, 1, v60
	v_readlane_b32 s12, v255, 15
	v_lshlrev_b64 v[24:25], 13, v[58:59]
	v_and_b32_e32 v0, 24, v0
	v_bfe_u32 v27, v60, 2, 2
	v_lshl_add_u32 v32, v26, 5, s12
	v_lshlrev_b32_e32 v26, 4, v26
	s_waitcnt lgkmcnt(0)
	v_lshl_add_u64 v[24:25], s[14:15], 0, v[24:25]
	v_or_b32_e32 v28, v0, v27
	v_and_b32_e32 v29, 24, v41
	v_ashrrev_i32_e32 v27, 31, v26
	v_lshl_add_u64 v[24:25], v[26:27], 1, v[24:25]
	v_mad_u32_u24 v41, v28, s10, v29
	v_readlane_b32 s12, v255, 16
	v_lshl_add_u64 v[24:25], v[24:25], 0, v[0:1]
	s_mov_b64 s[14:15], 0xc300000
	v_add_u32_e32 v42, v41, v32
	v_lshl_add_u32 v0, v39, 5, s12
	v_lshl_add_u64 v[36:37], v[24:25], 0, s[14:15]
	v_add_u32_e32 v33, v41, v0
	v_add_u32_e32 v43, 0x240, v42
	ds_read_b64_tr_b16 v[24:25], v42
	ds_read_b64_tr_b16 v[26:27], v43
	s_waitcnt lgkmcnt(0)
	v_add_u32_e32 v34, 0x240, v33
	ds_read_b64_tr_b16 v[28:29], v33
	ds_read_b64_tr_b16 v[30:31], v34
	s_waitcnt lgkmcnt(0)
	v_add_u32_e32 v44, 0x1200, v41
	v_mfma_f32_16x16x32_bf16 v[24:27], v[24:27], v[28:31], 0
	v_add_u32_e32 v45, v44, v32
	v_add_u32_e32 v0, v44, v0
	v_add_u32_e32 v46, 0x240, v45
	ds_read_b64_tr_b16 v[28:29], v45
	ds_read_b64_tr_b16 v[30:31], v46
	s_waitcnt lgkmcnt(0)
	v_add_u32_e32 v47, 0x240, v0
	ds_read_b64_tr_b16 v[32:33], v0
	ds_read_b64_tr_b16 v[34:35], v47
	s_waitcnt lgkmcnt(0)
	v_and_b32_e32 v38, 15, v60
	v_mfma_f32_16x16x32_bf16 v[24:27], v[28:31], v[32:35], v[24:27]
	v_lshlrev_b32_e32 v38, 7, v38
	v_lshl_or_b32 v0, v39, 11, v38
	s_andn2_b64 vcc, exec, s[22:23]
	s_nop 4
	v_cvt_pk_bf16_f32 v24, v24, v25
	v_cvt_pk_bf16_f32 v25, v26, v27
	v_lshl_add_u64 v[26:27], v[36:37], 0, v[0:1]
	v_or_b32_e32 v0, 1, v39
	global_store_dwordx2 v[26:27], v[24:25], off
	v_lshl_add_u32 v32, v0, 5, s12
	v_add_u32_e32 v33, v41, v32
	ds_read_b64_tr_b16 v[24:25], v42
	ds_read_b64_tr_b16 v[26:27], v43
	s_waitcnt lgkmcnt(0)
	v_add_u32_e32 v34, 0x240, v33
	ds_read_b64_tr_b16 v[28:29], v33
	ds_read_b64_tr_b16 v[30:31], v34
	s_waitcnt lgkmcnt(0)
	v_add_u32_e32 v39, v44, v32
	v_mfma_f32_16x16x32_bf16 v[24:27], v[24:27], v[28:31], 0
	ds_read_b64_tr_b16 v[28:29], v45
	ds_read_b64_tr_b16 v[30:31], v46
	s_waitcnt lgkmcnt(0)
	v_add_u32_e32 v41, 0x240, v39
	ds_read_b64_tr_b16 v[32:33], v39
	ds_read_b64_tr_b16 v[34:35], v41
	s_waitcnt lgkmcnt(0)
	v_lshl_or_b32 v0, v0, 11, v38
	v_mfma_f32_16x16x32_bf16 v[24:27], v[28:31], v[32:35], v[24:27]
	s_nop 7
	v_cvt_pk_bf16_f32 v24, v24, v25
	v_cvt_pk_bf16_f32 v25, v26, v27
	v_lshl_add_u64 v[26:27], v[36:37], 0, v[0:1]
	global_store_dwordx2 v[26:27], v[24:25], off
	s_waitcnt lgkmcnt(0)
	s_barrier
	s_cbranch_vccnz .LBB0_690
	s_and_saveexec_b64 s[14:15], s[40:41]
	s_cbranch_execz .LBB0_689
	s_waitcnt vmcnt(2)
	v_readlane_b32 s12, v255, 7
	s_nop 1
	v_mov_b32_e32 v0, s12
	v_readlane_b32 s12, v255, 8
	ds_write_b32 v0, v99
	s_nop 0
	v_mov_b32_e32 v0, s12
	ds_write_b32 v0, v98
	s_branch .LBB0_689
